# w_down, w_branch_a/b, w_out conversions moved from P0 into idle GEMM tails (WGs 128-255) + rsq epilogues
# speedup vs baseline: 1.0007x; 1.0007x over previous
; #define LAS __attribute__((address_space(3)))
; __device__ __forceinline__ void tr_load(const float* W, int N, int item, int lane, float (&wv)[32]) {
;     const int nblk = N / 32, kb = item / nblk, nb = item % nblk, k0 = 64 * kb, n0 = 32 * nb;
; #pragma unroll
;     for (int i = 0; i < 32; ++i) { const int kk = 2 * i + (lane >> 5); wv[i] = __builtin_nontemporal_load(W + (size_t)(k0 + kk) * N + n0 + (lane & 31)); }
; template <int MAP, bool HASG = false, bool PERMW = false>
; __device__ __forceinline__ void transpose_mat(const float* W, int K, int N, bf16_t* WT, LAS float* scr, int gw, int ngw, int lane, const float* gk = nullptr) {
;     const int nitems = (K / 64) * (N / 32);
;     int it = gw;
;     if (it >= nitems) return;
;     float wv[32];
;     tr_load(W, N, it, lane, wv);
.LBB0_50:
	s_cmpk_gt_i32 s6, 0x3ff
	s_branch .LBB0_57
	s_add_u32 s12, s7, 0x7600000
	v_readlane_b32 s56, v254, 60
	s_addc_u32 s13, s25, 0
	s_lshl_b64 s[14:15], s[36:37], 23
	v_readlane_b32 s70, v255, 10
	v_readlane_b32 s71, v255, 11
	s_add_u32 s14, s70, s14
	s_addc_u32 s15, s71, s15
	s_ashr_i32 s16, s6, 31
	s_lshr_b32 s16, s16, 26
	s_add_i32 s16, s6, s16
	s_and_b32 s17, s16, 0xffffffc0
	s_sub_i32 s16, s6, s17
	s_lshl_b32 s16, s16, 5
	v_or_b32_e32 v32, s17, v134
	s_ashr_i32 s17, s16, 31
	s_lshl_b64 s[16:17], s[16:17], 2
	s_add_u32 s16, s14, s16
	s_waitcnt vmcnt(0)
	v_or_b32_e32 v2, 2, v32
	s_addc_u32 s17, s15, s17
	v_mov_b32_e32 v49, v193
	v_ashrrev_i32_e32 v33, 31, v32
	s_waitcnt vmcnt(32)
	v_ashrrev_i32_e32 v3, 31, v2
	v_lshl_add_u64 v[34:35], s[16:17], 0, v[48:49]
	v_lshlrev_b64 v[0:1], 13, v[32:33]
	v_lshlrev_b64 v[2:3], 13, v[2:3]
	v_lshl_add_u64 v[0:1], v[34:35], 0, v[0:1]
	v_lshl_add_u64 v[2:3], v[34:35], 0, v[2:3]
	global_load_dword v0, v[0:1], off nt
	s_waitcnt vmcnt(32)
	v_or_b32_e32 v4, 6, v32
	global_load_dword v1, v[2:3], off nt
	v_or_b32_e32 v2, 4, v32
	v_ashrrev_i32_e32 v3, 31, v2
	s_waitcnt vmcnt(32)
	v_ashrrev_i32_e32 v5, 31, v4
	v_lshlrev_b64 v[2:3], 13, v[2:3]
	v_lshlrev_b64 v[4:5], 13, v[4:5]
	v_lshl_add_u64 v[2:3], v[34:35], 0, v[2:3]
	v_lshl_add_u64 v[4:5], v[34:35], 0, v[4:5]
	global_load_dword v2, v[2:3], off nt
	s_waitcnt vmcnt(32)
	v_or_b32_e32 v6, 10, v32
	global_load_dword v3, v[4:5], off nt
	v_or_b32_e32 v4, 8, v32
	v_ashrrev_i32_e32 v5, 31, v4
	s_waitcnt vmcnt(32)
	v_ashrrev_i32_e32 v7, 31, v6
	v_lshlrev_b64 v[4:5], 13, v[4:5]
	v_lshlrev_b64 v[6:7], 13, v[6:7]
	v_lshl_add_u64 v[4:5], v[34:35], 0, v[4:5]
	v_lshl_add_u64 v[6:7], v[34:35], 0, v[6:7]
	global_load_dword v4, v[4:5], off nt
	s_waitcnt vmcnt(32)
	v_or_b32_e32 v8, 14, v32
	global_load_dword v5, v[6:7], off nt
	v_or_b32_e32 v6, 12, v32
	v_ashrrev_i32_e32 v7, 31, v6
	s_waitcnt vmcnt(32)
	v_ashrrev_i32_e32 v9, 31, v8
	v_lshlrev_b64 v[6:7], 13, v[6:7]
	v_lshlrev_b64 v[8:9], 13, v[8:9]
	v_lshl_add_u64 v[6:7], v[34:35], 0, v[6:7]
	v_lshl_add_u64 v[8:9], v[34:35], 0, v[8:9]
	global_load_dword v6, v[6:7], off nt
	s_waitcnt vmcnt(32)
	v_or_b32_e32 v10, 18, v32
	global_load_dword v7, v[8:9], off nt
	v_or_b32_e32 v8, 16, v32
	v_ashrrev_i32_e32 v9, 31, v8
	s_waitcnt vmcnt(32)
	v_ashrrev_i32_e32 v11, 31, v10
	v_lshlrev_b64 v[8:9], 13, v[8:9]
	v_lshlrev_b64 v[10:11], 13, v[10:11]
	v_lshl_add_u64 v[8:9], v[34:35], 0, v[8:9]
	v_lshl_add_u64 v[10:11], v[34:35], 0, v[10:11]
	global_load_dword v8, v[8:9], off nt
	s_waitcnt vmcnt(32)
	v_or_b32_e32 v12, 22, v32
	global_load_dword v9, v[10:11], off nt
	v_or_b32_e32 v10, 20, v32
	v_ashrrev_i32_e32 v11, 31, v10
	s_waitcnt vmcnt(32)
	v_ashrrev_i32_e32 v13, 31, v12
	v_lshlrev_b64 v[10:11], 13, v[10:11]
	v_lshlrev_b64 v[12:13], 13, v[12:13]
	v_lshl_add_u64 v[10:11], v[34:35], 0, v[10:11]
	v_lshl_add_u64 v[12:13], v[34:35], 0, v[12:13]
	global_load_dword v10, v[10:11], off nt
	s_waitcnt vmcnt(32)
	v_or_b32_e32 v14, 26, v32
	global_load_dword v11, v[12:13], off nt
	v_or_b32_e32 v12, 24, v32
	v_ashrrev_i32_e32 v13, 31, v12
	s_waitcnt vmcnt(32)
	v_ashrrev_i32_e32 v15, 31, v14
	v_lshlrev_b64 v[12:13], 13, v[12:13]
	v_lshlrev_b64 v[14:15], 13, v[14:15]
	v_lshl_add_u64 v[12:13], v[34:35], 0, v[12:13]
	v_lshl_add_u64 v[14:15], v[34:35], 0, v[14:15]
	global_load_dword v12, v[12:13], off nt
	s_waitcnt vmcnt(32)
	v_or_b32_e32 v16, 30, v32
	global_load_dword v13, v[14:15], off nt
	v_or_b32_e32 v14, 28, v32
	v_ashrrev_i32_e32 v15, 31, v14
	s_waitcnt vmcnt(32)
	v_ashrrev_i32_e32 v17, 31, v16
	v_lshlrev_b64 v[14:15], 13, v[14:15]
	v_lshlrev_b64 v[16:17], 13, v[16:17]
	v_lshl_add_u64 v[14:15], v[34:35], 0, v[14:15]
	v_lshl_add_u64 v[16:17], v[34:35], 0, v[16:17]
	global_load_dword v14, v[14:15], off nt
	s_waitcnt vmcnt(32)
	v_or_b32_e32 v18, 34, v32
	global_load_dword v15, v[16:17], off nt
	v_or_b32_e32 v16, 32, v32
	v_ashrrev_i32_e32 v17, 31, v16
	s_waitcnt vmcnt(32)
; #define LAS __attribute__((address_space(3)))
; __device__ __forceinline__ unsigned pk2(float lo, float hi) { f32x2 f = {lo, hi}; bf16x2_t b = __builtin_convertvector(f, bf16x2_t); return __builtin_bit_cast(unsigned, b); }
; __device__ __forceinline__ void tr_load(const float* W, int N, int item, int lane, float (&wv)[32]) {
;     const int nblk = N / 32, kb = item / nblk, nb = item % nblk, k0 = 64 * kb, n0 = 32 * nb;
; #pragma unroll
;     for (int i = 0; i < 32; ++i) { const int kk = 2 * i + (lane >> 5); wv[i] = __builtin_nontemporal_load(W + (size_t)(k0 + kk) * N + n0 + (lane & 31)); }
; template <int MAP, bool HASG, bool PERMW>
; __device__ __forceinline__ void tr_store(int K, int N, bf16_t* WT, LAS float* scr, int item, int lane, const float* gk) {
;     const int nblk = N / 32, kb = item / nblk, nb = item % nblk, k0 = 64 * kb, n0 = 32 * nb;
;     asm volatile("s_waitcnt lgkmcnt(0)" ::: "memory");
;     const int c = lane & 7;
;     f32x4 g0 = {1.f, 1.f, 1.f, 1.f}, g1 = {1.f, 1.f, 1.f, 1.f};
;     if (HASG) { g0 = *(const f32x4*)(gk + k0 + 8 * c); g1 = *(const f32x4*)(gk + k0 + 8 * c + 4); }
; #pragma unroll
;     for (int j = 0; j < 4; ++j) { const int n = (lane >> 3) + 8 * j; const LAS float* s = scr + (8 * c) * 33 + n;
;         u32x4 o; o.x = pk2(s[0 * 33] * g0[0], s[1 * 33] * g0[1]); o.y = pk2(s[2 * 33] * g0[2], s[3 * 33] * g0[3]); o.z = pk2(s[4 * 33] * g1[0], s[5 * 33] * g1[1]); o.w = pk2(s[6 * 33] * g1[2], s[7 * 33] * g1[3]);
;         const int wr_ = rowmap<MAP>(n0 + n), slot_ = PERMW ? ((wr_ & ~31) + invperm32(wr_ & 31)) : wr_;
;         *(u32x4*)((char*)WT + tiled_off(slot_, k0 + 8 * c, K / 64)) = o; }
	v_ashrrev_i32_e32 v19, 31, v18
	v_lshlrev_b64 v[16:17], 13, v[16:17]
	v_lshlrev_b64 v[18:19], 13, v[18:19]
	v_lshl_add_u64 v[16:17], v[34:35], 0, v[16:17]
	v_lshl_add_u64 v[18:19], v[34:35], 0, v[18:19]
	global_load_dword v16, v[16:17], off nt
	s_waitcnt vmcnt(32)
	v_or_b32_e32 v20, 38, v32
	global_load_dword v17, v[18:19], off nt
	v_or_b32_e32 v18, 36, v32
	v_ashrrev_i32_e32 v19, 31, v18
	s_waitcnt vmcnt(32)
	v_ashrrev_i32_e32 v21, 31, v20
	v_lshlrev_b64 v[18:19], 13, v[18:19]
	v_lshlrev_b64 v[20:21], 13, v[20:21]
	v_lshl_add_u64 v[18:19], v[34:35], 0, v[18:19]
	v_lshl_add_u64 v[20:21], v[34:35], 0, v[20:21]
	global_load_dword v18, v[18:19], off nt
	s_waitcnt vmcnt(32)
	v_or_b32_e32 v22, 42, v32
	global_load_dword v19, v[20:21], off nt
	v_or_b32_e32 v20, 40, v32
	v_ashrrev_i32_e32 v21, 31, v20
	s_waitcnt vmcnt(32)
	v_ashrrev_i32_e32 v23, 31, v22
	v_lshlrev_b64 v[20:21], 13, v[20:21]
	v_lshlrev_b64 v[22:23], 13, v[22:23]
	v_lshl_add_u64 v[20:21], v[34:35], 0, v[20:21]
	v_lshl_add_u64 v[22:23], v[34:35], 0, v[22:23]
	global_load_dword v20, v[20:21], off nt
	s_waitcnt vmcnt(32)
	v_or_b32_e32 v24, 46, v32
	global_load_dword v21, v[22:23], off nt
	v_or_b32_e32 v22, 44, v32
	v_ashrrev_i32_e32 v23, 31, v22
	s_waitcnt vmcnt(32)
	v_ashrrev_i32_e32 v25, 31, v24
	v_lshlrev_b64 v[22:23], 13, v[22:23]
	v_lshlrev_b64 v[24:25], 13, v[24:25]
	v_lshl_add_u64 v[22:23], v[34:35], 0, v[22:23]
	v_lshl_add_u64 v[24:25], v[34:35], 0, v[24:25]
	global_load_dword v22, v[22:23], off nt
	s_waitcnt vmcnt(32)
	v_or_b32_e32 v26, 50, v32
	global_load_dword v23, v[24:25], off nt
	v_or_b32_e32 v24, 48, v32
	v_ashrrev_i32_e32 v25, 31, v24
	s_waitcnt vmcnt(32)
	v_ashrrev_i32_e32 v27, 31, v26
	v_lshlrev_b64 v[24:25], 13, v[24:25]
	v_lshlrev_b64 v[26:27], 13, v[26:27]
	v_lshl_add_u64 v[24:25], v[34:35], 0, v[24:25]
	v_lshl_add_u64 v[26:27], v[34:35], 0, v[26:27]
	global_load_dword v24, v[24:25], off nt
	s_waitcnt vmcnt(32)
	v_or_b32_e32 v28, 54, v32
	global_load_dword v25, v[26:27], off nt
	v_or_b32_e32 v26, 52, v32
	v_ashrrev_i32_e32 v27, 31, v26
	s_waitcnt vmcnt(32)
	v_ashrrev_i32_e32 v29, 31, v28
	v_lshlrev_b64 v[26:27], 13, v[26:27]
	v_lshlrev_b64 v[28:29], 13, v[28:29]
	v_lshl_add_u64 v[26:27], v[34:35], 0, v[26:27]
	v_lshl_add_u64 v[28:29], v[34:35], 0, v[28:29]
	global_load_dword v26, v[26:27], off nt
	s_waitcnt vmcnt(32)
	v_or_b32_e32 v30, 58, v32
	global_load_dword v27, v[28:29], off nt
	v_or_b32_e32 v28, 56, v32
	v_ashrrev_i32_e32 v29, 31, v28
	s_waitcnt vmcnt(32)
	v_ashrrev_i32_e32 v31, 31, v30
	v_lshlrev_b64 v[28:29], 13, v[28:29]
	v_lshlrev_b64 v[30:31], 13, v[30:31]
	v_lshl_add_u64 v[28:29], v[34:35], 0, v[28:29]
	v_lshl_add_u64 v[30:31], v[34:35], 0, v[30:31]
	global_load_dword v28, v[28:29], off nt
	s_lshl_b32 s20, s6, 5
	global_load_dword v29, v[30:31], off nt
	v_or_b32_e32 v30, 60, v32
	v_or_b32_e32 v32, 62, v32
	v_ashrrev_i32_e32 v31, 31, v30
	v_ashrrev_i32_e32 v33, 31, v32
	v_lshlrev_b64 v[30:31], 13, v[30:31]
	v_lshlrev_b64 v[32:33], 13, v[32:33]
	v_lshl_add_u64 v[30:31], v[34:35], 0, v[30:31]
	v_lshl_add_u64 v[32:33], v[34:35], 0, v[32:33]
	global_load_dword v30, v[30:31], off nt
	v_lshlrev_b32_e32 v35, 3, v132
	global_load_dword v31, v[32:33], off nt
	v_and_b32_e32 v35, 56, v35
	v_mul_u32_u24_e32 v35, 0x84, v35
	v_add3_u32 v38, s26, v35, v139
	v_lshlrev_b32_e32 v35, 4, v132
	v_bitop3_b32 v40, v139, 19, v138 bitop3:0xc8
	v_add_u32_e32 v34, s26, v48
	v_and_b32_e32 v39, 48, v35
	v_or_b32_e32 v35, s20, v40
	v_lshl_add_u64 v[32:33], s[14:15], 0, v[48:49]
	v_lshlrev_b32_e32 v41, 6, v35
	s_lshl_b32 s18, s8, 11
	s_lshl_b32 s19, s8, 5
	v_add_u32_e32 v42, v34, v136
	s_mov_b32 s21, s6
	v_readlane_b32 s57, v254, 61
	v_readlane_b32 s58, v254, 62
	v_readlane_b32 s59, v254, 63
	v_readlane_b32 s60, v255, 0
	v_readlane_b32 s61, v255, 1
	v_readlane_b32 s62, v255, 2
	v_readlane_b32 s63, v255, 3
	v_readlane_b32 s64, v255, 4
	v_readlane_b32 s65, v255, 5
	v_readlane_b32 s66, v255, 6
	v_readlane_b32 s67, v255, 7
	v_readlane_b32 s68, v255, 8
	v_readlane_b32 s69, v255, 9
	s_branch .LBB0_53

; #define LAS __attribute__((address_space(3)))
; __device__ __forceinline__ void tr_load(const float* W, int N, int item, int lane, float (&wv)[32]) {
;     const int nblk = N / 32, kb = item / nblk, nb = item % nblk, k0 = 64 * kb, n0 = 32 * nb;
; #pragma unroll
;     for (int i = 0; i < 32; ++i) { const int kk = 2 * i + (lane >> 5); wv[i] = __builtin_nontemporal_load(W + (size_t)(k0 + kk) * N + n0 + (lane & 31)); }
; template <int MAP, bool HASG = false, bool PERMW = false>
; __device__ __forceinline__ void transpose_mat(const float* W, int K, int N, bf16_t* WT, LAS float* scr, int gw, int ngw, int lane, const float* gk = nullptr) {
;     const int nitems = (K / 64) * (N / 32);
;     int it = gw;
;     if (it >= nitems) return;
;     float wv[32];
;     tr_load(W, N, it, lane, wv);
.LBB0_57:
	s_cmpk_gt_i32 s6, 0x7ff
	s_branch .LBB0_70
	s_lshl_b64 s[14:15], s[36:37], 22
	s_add_u32 s29, s7, 0x7a00000
	s_addc_u32 s30, s25, 0
	s_lshl_b64 s[12:13], s[36:37], 24
	v_readlane_b32 s56, v254, 0
	v_readlane_b32 s57, v254, 1
	s_add_u32 s18, s56, s12
	s_addc_u32 s19, s57, s13
	s_ashr_i32 s12, s6, 31
	s_lshr_b32 s12, s12, 26
	s_add_i32 s12, s6, s12
	s_and_b32 s13, s12, 0xffffffc0
	s_sub_i32 s12, s6, s13
	s_lshl_b32 s12, s12, 5
	v_or_b32_e32 v100, s13, v134
	s_ashr_i32 s13, s12, 31
	s_lshl_b64 s[16:17], s[12:13], 2
	s_add_u32 s12, s18, s16
	s_waitcnt vmcnt(0)
	v_or_b32_e32 v2, 2, v100
	s_addc_u32 s13, s19, s17
	v_mov_b32_e32 v47, v193
	v_ashrrev_i32_e32 v101, 31, v100
	s_waitcnt vmcnt(32)
	v_ashrrev_i32_e32 v3, 31, v2
	v_lshl_add_u64 v[102:103], s[12:13], 0, v[46:47]
	v_lshlrev_b64 v[32:33], 13, v[100:101]
	v_lshlrev_b64 v[34:35], 13, v[2:3]
	v_lshl_add_u64 v[0:1], v[102:103], 0, v[32:33]
	v_lshl_add_u64 v[2:3], v[102:103], 0, v[34:35]
	global_load_dword v0, v[0:1], off nt
	s_waitcnt vmcnt(32)
	v_or_b32_e32 v4, 6, v100
	global_load_dword v1, v[2:3], off nt
	v_or_b32_e32 v2, 4, v100
	v_ashrrev_i32_e32 v3, 31, v2
	s_waitcnt vmcnt(32)
	v_ashrrev_i32_e32 v5, 31, v4
	v_lshlrev_b64 v[36:37], 13, v[2:3]
	v_lshlrev_b64 v[38:39], 13, v[4:5]
	v_lshl_add_u64 v[2:3], v[102:103], 0, v[36:37]
	v_lshl_add_u64 v[4:5], v[102:103], 0, v[38:39]
	global_load_dword v2, v[2:3], off nt
	s_waitcnt vmcnt(32)
	v_or_b32_e32 v6, 10, v100
	global_load_dword v3, v[4:5], off nt
	v_or_b32_e32 v4, 8, v100
	v_ashrrev_i32_e32 v5, 31, v4
	s_waitcnt vmcnt(32)
	v_ashrrev_i32_e32 v7, 31, v6
	v_lshlrev_b64 v[40:41], 13, v[4:5]
	v_lshlrev_b64 v[42:43], 13, v[6:7]
	v_lshl_add_u64 v[4:5], v[102:103], 0, v[40:41]
	v_lshl_add_u64 v[6:7], v[102:103], 0, v[42:43]
	global_load_dword v4, v[4:5], off nt
	s_waitcnt vmcnt(32)
	v_or_b32_e32 v8, 14, v100
	global_load_dword v5, v[6:7], off nt
	v_or_b32_e32 v6, 12, v100
	v_ashrrev_i32_e32 v7, 31, v6
	s_waitcnt vmcnt(32)
	v_ashrrev_i32_e32 v9, 31, v8
	v_lshlrev_b64 v[50:51], 13, v[6:7]
	v_lshlrev_b64 v[52:53], 13, v[8:9]
	v_lshl_add_u64 v[6:7], v[102:103], 0, v[50:51]
	v_lshl_add_u64 v[8:9], v[102:103], 0, v[52:53]
	global_load_dword v6, v[6:7], off nt
	s_waitcnt vmcnt(32)
	v_or_b32_e32 v10, 18, v100
	global_load_dword v7, v[8:9], off nt
	v_or_b32_e32 v8, 16, v100
	v_ashrrev_i32_e32 v9, 31, v8
	s_waitcnt vmcnt(32)
	v_ashrrev_i32_e32 v11, 31, v10
	v_lshlrev_b64 v[54:55], 13, v[8:9]
	v_lshlrev_b64 v[56:57], 13, v[10:11]
	v_lshl_add_u64 v[8:9], v[102:103], 0, v[54:55]
	v_lshl_add_u64 v[10:11], v[102:103], 0, v[56:57]
	global_load_dword v8, v[8:9], off nt
	s_waitcnt vmcnt(32)
	v_or_b32_e32 v12, 22, v100
	global_load_dword v9, v[10:11], off nt
	v_or_b32_e32 v10, 20, v100
	v_ashrrev_i32_e32 v11, 31, v10
	s_waitcnt vmcnt(32)
	v_ashrrev_i32_e32 v13, 31, v12
	v_lshlrev_b64 v[58:59], 13, v[10:11]
	v_lshlrev_b64 v[60:61], 13, v[12:13]
	v_lshl_add_u64 v[10:11], v[102:103], 0, v[58:59]
	v_lshl_add_u64 v[12:13], v[102:103], 0, v[60:61]
	global_load_dword v10, v[10:11], off nt
	s_waitcnt vmcnt(32)
	v_or_b32_e32 v14, 26, v100
	global_load_dword v11, v[12:13], off nt
	v_or_b32_e32 v12, 24, v100
	v_ashrrev_i32_e32 v13, 31, v12
	s_waitcnt vmcnt(32)
	v_ashrrev_i32_e32 v15, 31, v14
	v_lshlrev_b64 v[62:63], 13, v[12:13]
	v_lshlrev_b64 v[64:65], 13, v[14:15]
	v_lshl_add_u64 v[12:13], v[102:103], 0, v[62:63]
	v_lshl_add_u64 v[14:15], v[102:103], 0, v[64:65]
	global_load_dword v12, v[12:13], off nt
	s_waitcnt vmcnt(32)
	v_or_b32_e32 v16, 30, v100
	global_load_dword v13, v[14:15], off nt
	v_or_b32_e32 v14, 28, v100
	v_ashrrev_i32_e32 v15, 31, v14
	s_waitcnt vmcnt(32)
	v_ashrrev_i32_e32 v17, 31, v16
	v_lshlrev_b64 v[66:67], 13, v[14:15]
	v_lshlrev_b64 v[68:69], 13, v[16:17]
	v_lshl_add_u64 v[14:15], v[102:103], 0, v[66:67]
	v_lshl_add_u64 v[16:17], v[102:103], 0, v[68:69]
	global_load_dword v14, v[14:15], off nt
	s_waitcnt vmcnt(32)
	v_or_b32_e32 v18, 34, v100
	global_load_dword v15, v[16:17], off nt
	v_or_b32_e32 v16, 32, v100
	v_ashrrev_i32_e32 v17, 31, v16
	s_waitcnt vmcnt(32)
; #define LAS __attribute__((address_space(3)))
; __device__ __forceinline__ unsigned pk2(float lo, float hi) { f32x2 f = {lo, hi}; bf16x2_t b = __builtin_convertvector(f, bf16x2_t); return __builtin_bit_cast(unsigned, b); }
; __device__ __forceinline__ void tr_load(const float* W, int N, int item, int lane, float (&wv)[32]) {
;     const int nblk = N / 32, kb = item / nblk, nb = item % nblk, k0 = 64 * kb, n0 = 32 * nb;
; #pragma unroll
;     for (int i = 0; i < 32; ++i) { const int kk = 2 * i + (lane >> 5); wv[i] = __builtin_nontemporal_load(W + (size_t)(k0 + kk) * N + n0 + (lane & 31)); }
; template <int MAP, bool HASG, bool PERMW>
; __device__ __forceinline__ void tr_store(int K, int N, bf16_t* WT, LAS float* scr, int item, int lane, const float* gk) {
;     const int nblk = N / 32, kb = item / nblk, nb = item % nblk, k0 = 64 * kb, n0 = 32 * nb;
;     asm volatile("s_waitcnt lgkmcnt(0)" ::: "memory");
;     const int c = lane & 7;
;     f32x4 g0 = {1.f, 1.f, 1.f, 1.f}, g1 = {1.f, 1.f, 1.f, 1.f};
;     if (HASG) { g0 = *(const f32x4*)(gk + k0 + 8 * c); g1 = *(const f32x4*)(gk + k0 + 8 * c + 4); }
; #pragma unroll
;     for (int j = 0; j < 4; ++j) { const int n = (lane >> 3) + 8 * j; const LAS float* s = scr + (8 * c) * 33 + n;
;         u32x4 o; o.x = pk2(s[0 * 33] * g0[0], s[1 * 33] * g0[1]); o.y = pk2(s[2 * 33] * g0[2], s[3 * 33] * g0[3]); o.z = pk2(s[4 * 33] * g1[0], s[5 * 33] * g1[1]); o.w = pk2(s[6 * 33] * g1[2], s[7 * 33] * g1[3]);
;         const int wr_ = rowmap<MAP>(n0 + n), slot_ = PERMW ? ((wr_ & ~31) + invperm32(wr_ & 31)) : wr_;
;         *(u32x4*)((char*)WT + tiled_off(slot_, k0 + 8 * c, K / 64)) = o; }
	v_ashrrev_i32_e32 v19, 31, v18
	v_lshlrev_b64 v[70:71], 13, v[16:17]
	v_lshlrev_b64 v[72:73], 13, v[18:19]
	v_lshl_add_u64 v[16:17], v[102:103], 0, v[70:71]
	v_lshl_add_u64 v[18:19], v[102:103], 0, v[72:73]
	global_load_dword v16, v[16:17], off nt
	s_waitcnt vmcnt(32)
	v_or_b32_e32 v20, 38, v100
	global_load_dword v17, v[18:19], off nt
	v_or_b32_e32 v18, 36, v100
	v_ashrrev_i32_e32 v19, 31, v18
	s_waitcnt vmcnt(32)
	v_ashrrev_i32_e32 v21, 31, v20
	v_lshlrev_b64 v[74:75], 13, v[18:19]
	v_lshlrev_b64 v[76:77], 13, v[20:21]
	v_lshl_add_u64 v[18:19], v[102:103], 0, v[74:75]
	v_lshl_add_u64 v[20:21], v[102:103], 0, v[76:77]
	global_load_dword v18, v[18:19], off nt
	s_waitcnt vmcnt(32)
	v_or_b32_e32 v22, 42, v100
	global_load_dword v19, v[20:21], off nt
	v_or_b32_e32 v20, 40, v100
	v_ashrrev_i32_e32 v21, 31, v20
	s_waitcnt vmcnt(32)
	v_ashrrev_i32_e32 v23, 31, v22
	v_lshlrev_b64 v[78:79], 13, v[20:21]
	v_lshlrev_b64 v[80:81], 13, v[22:23]
	v_lshl_add_u64 v[20:21], v[102:103], 0, v[78:79]
	v_lshl_add_u64 v[22:23], v[102:103], 0, v[80:81]
	global_load_dword v20, v[20:21], off nt
	s_waitcnt vmcnt(32)
	v_or_b32_e32 v24, 46, v100
	global_load_dword v21, v[22:23], off nt
	v_or_b32_e32 v22, 44, v100
	v_ashrrev_i32_e32 v23, 31, v22
	s_waitcnt vmcnt(32)
	v_ashrrev_i32_e32 v25, 31, v24
	v_lshlrev_b64 v[82:83], 13, v[22:23]
	v_lshlrev_b64 v[84:85], 13, v[24:25]
	v_lshl_add_u64 v[22:23], v[102:103], 0, v[82:83]
	v_lshl_add_u64 v[24:25], v[102:103], 0, v[84:85]
	global_load_dword v22, v[22:23], off nt
	s_waitcnt vmcnt(32)
	v_or_b32_e32 v26, 50, v100
	global_load_dword v23, v[24:25], off nt
	v_or_b32_e32 v24, 48, v100
	v_ashrrev_i32_e32 v25, 31, v24
	s_waitcnt vmcnt(32)
	v_ashrrev_i32_e32 v27, 31, v26
	v_lshlrev_b64 v[86:87], 13, v[24:25]
	v_lshlrev_b64 v[88:89], 13, v[26:27]
	v_lshl_add_u64 v[24:25], v[102:103], 0, v[86:87]
	v_lshl_add_u64 v[26:27], v[102:103], 0, v[88:89]
	global_load_dword v24, v[24:25], off nt
	s_waitcnt vmcnt(32)
	v_or_b32_e32 v28, 54, v100
	global_load_dword v25, v[26:27], off nt
	v_or_b32_e32 v26, 52, v100
	v_ashrrev_i32_e32 v27, 31, v26
	s_waitcnt vmcnt(32)
	v_ashrrev_i32_e32 v29, 31, v28
	v_lshlrev_b64 v[90:91], 13, v[26:27]
	v_lshlrev_b64 v[92:93], 13, v[28:29]
	v_lshl_add_u64 v[26:27], v[102:103], 0, v[90:91]
	v_lshl_add_u64 v[28:29], v[102:103], 0, v[92:93]
	global_load_dword v26, v[26:27], off nt
	s_waitcnt vmcnt(32)
	v_or_b32_e32 v30, 58, v100
	global_load_dword v27, v[28:29], off nt
	v_or_b32_e32 v28, 56, v100
	v_ashrrev_i32_e32 v29, 31, v28
	s_waitcnt vmcnt(32)
	v_ashrrev_i32_e32 v31, 31, v30
	v_lshlrev_b64 v[94:95], 13, v[28:29]
	v_lshlrev_b64 v[96:97], 13, v[30:31]
	v_lshl_add_u64 v[28:29], v[102:103], 0, v[94:95]
	v_lshl_add_u64 v[30:31], v[102:103], 0, v[96:97]
	global_load_dword v28, v[28:29], off nt
	s_lshl_b32 s28, s6, 5
	global_load_dword v29, v[30:31], off nt
	v_or_b32_e32 v30, 60, v100
	v_or_b32_e32 v100, 62, v100
	v_ashrrev_i32_e32 v31, 31, v30
	v_ashrrev_i32_e32 v101, 31, v100
	v_lshlrev_b64 v[98:99], 13, v[30:31]
	v_lshlrev_b64 v[100:101], 13, v[100:101]
	v_lshl_add_u64 v[30:31], v[102:103], 0, v[98:99]
	v_lshl_add_u64 v[102:103], v[102:103], 0, v[100:101]
	global_load_dword v30, v[30:31], off nt
	v_bitop3_b32 v116, v139, 19, v138 bitop3:0xc8
	global_load_dword v31, v[102:103], off nt
	v_lshl_add_u64 v[102:103], s[18:19], 0, v[46:47]
	v_lshlrev_b32_e32 v47, 3, v132
	v_and_b32_e32 v47, 56, v47
	v_add_u32_e32 v104, s26, v46
	v_mul_u32_u24_e32 v47, 0x84, v47
	v_lshlrev_b32_e32 v49, 4, v132
	v_or_b32_e32 v105, s28, v116
	v_add3_u32 v47, s26, v47, v139
	v_and_b32_e32 v49, 48, v49
	v_lshlrev_b32_e32 v117, 6, v105
	s_lshl_b32 s12, s8, 11
	s_lshl_b32 s13, s8, 5
	v_add_u32_e32 v108, v104, v136
	s_mov_b32 s31, s28
	s_mov_b32 s34, s6
	v_readlane_b32 s58, v254, 2
	v_readlane_b32 s59, v254, 3
	v_readlane_b32 s60, v254, 4
	v_readlane_b32 s61, v254, 5
	v_readlane_b32 s62, v254, 6
	v_readlane_b32 s63, v254, 7
	v_readlane_b32 s64, v254, 8
	v_readlane_b32 s65, v254, 9
	v_readlane_b32 s66, v254, 10
	v_readlane_b32 s67, v254, 11
	v_readlane_b32 s68, v254, 12
	v_readlane_b32 s69, v254, 13
	v_readlane_b32 s70, v254, 14
	v_readlane_b32 s71, v254, 15
	s_branch .LBB0_60

; #define LAS __attribute__((address_space(3)))
; __device__ __forceinline__ unsigned pk2(float lo, float hi) { f32x2 f = {lo, hi}; bf16x2_t b = __builtin_convertvector(f, bf16x2_t); return __builtin_bit_cast(unsigned, b); }
; __device__ __forceinline__ size_t tiled_off(int row, int col, int nkt) {
;     return ((size_t)(row >> 7) * nkt + (col >> 6)) * 16384 + (size_t)pg8::lds_byte(row & 127, col & 63);
; }
; template <int MAP, bool HASG, bool PERMW>
; __device__ __forceinline__ void tr_store(int K, int N, bf16_t* WT, LAS float* scr, int item, int lane, const float* gk) {
;     const int nblk = N / 32, kb = item / nblk, nb = item % nblk, k0 = 64 * kb, n0 = 32 * nb;
;     asm volatile("s_waitcnt lgkmcnt(0)" ::: "memory");
;     const int c = lane & 7;
;     f32x4 g0 = {1.f, 1.f, 1.f, 1.f}, g1 = {1.f, 1.f, 1.f, 1.f};
;     if (HASG) { g0 = *(const f32x4*)(gk + k0 + 8 * c); g1 = *(const f32x4*)(gk + k0 + 8 * c + 4); }
; #pragma unroll
;     for (int j = 0; j < 4; ++j) { const int n = (lane >> 3) + 8 * j; const LAS float* s = scr + (8 * c) * 33 + n;
;         u32x4 o; o.x = pk2(s[0 * 33] * g0[0], s[1 * 33] * g0[1]); o.y = pk2(s[2 * 33] * g0[2], s[3 * 33] * g0[3]); o.z = pk2(s[4 * 33] * g1[0], s[5 * 33] * g1[1]); o.w = pk2(s[6 * 33] * g1[2], s[7 * 33] * g1[3]);
;         const int wr_ = rowmap<MAP>(n0 + n), slot_ = PERMW ? ((wr_ & ~31) + invperm32(wr_ & 31)) : wr_;
;         *(u32x4*)((char*)WT + tiled_off(slot_, k0 + 8 * c, K / 64)) = o; }
.LBB0_158:
	s_cmpk_lt_u32 s2, 0x80
	s_cbranch_scc1 .Ltc1_done
	v_writelane_b32 v255, s4, 24
	v_writelane_b32 v255, s5, 25
	v_writelane_b32 v255, s6, 26
	v_writelane_b32 v255, s7, 27
	v_writelane_b32 v255, s8, 28
	v_writelane_b32 v255, s9, 29
	v_writelane_b32 v255, s10, 30
	v_writelane_b32 v255, s11, 31
	v_writelane_b32 v255, s12, 32
	v_writelane_b32 v255, s13, 33
	v_writelane_b32 v255, s14, 34
	v_writelane_b32 v255, s15, 35
	v_writelane_b32 v255, s16, 36
	v_writelane_b32 v255, s17, 37
	v_writelane_b32 v255, s18, 38
	v_writelane_b32 v255, s19, 39
	v_readfirstlane_b32 s8, v234
	s_nop 3
	s_lshr_b32 s8, s8, 6
	s_sub_u32 s18, s2, 0x80
	s_lshl_b32 s18, s18, 3
	s_add_u32 s18, s18, s8
	s_mul_i32 s10, s8, 0x2100
	v_and_b32_e32 v0, 63, v234
	v_and_b32_e32 v1, 31, v0
	v_lshrrev_b32_e32 v2, 5, v0
	v_lshlrev_b32_e32 v3, 13, v2
	v_lshl_add_u32 v3, v1, 2, v3
	v_mul_u32_u24_e32 v4, 33, v2
	v_add_u32_e32 v4, v4, v1
	v_lshl_add_u32 v4, v4, 2, s10
	v_and_b32_e32 v5, 7, v0
	v_lshrrev_b32_e32 v6, 3, v0
	v_mul_u32_u24_e32 v7, 0x108, v5
	v_add_u32_e32 v7, v7, v6
	v_lshl_add_u32 v7, v7, 2, s10
	v_lshrrev_b32_e32 v12, 2, v5
	v_lshlrev_b32_e32 v12, 10, v12
	v_and_b32_e32 v13, 3, v5
	v_lshl_add_u32 v12, v13, 4, v12
	v_lshl_add_u32 v8, v6, 6, v12
	v_xor_b32_e32 v9, 32, v8
	v_add_u32_e32 v9, 0x200, v9
	v_and_b32_e32 v13, 3, v6
	v_lshl_add_u32 v10, v13, 6, v12
	v_bfe_u32 v13, v6, 2, 1
	v_lshl_add_u32 v10, v13, 11, v10
	v_xor_b32_e32 v11, 32, v10
	v_readlane_b32 s4, v255, 4
	v_readlane_b32 s5, v255, 5
	s_nop 3
	s_and_b32 s6, s60, 0x2c00000
	s_add_u32 s4, s4, s6
	s_addc_u32 s5, s5, 0
	s_add_u32 s6, s76, 0x2c00000
	s_addc_u32 s7, s77, 0
	s_mov_b32 s9, s18

; #define LAS __attribute__((address_space(3)))
; __device__ __forceinline__ unsigned pk2(float lo, float hi) { f32x2 f = {lo, hi}; bf16x2_t b = __builtin_convertvector(f, bf16x2_t); return __builtin_bit_cast(unsigned, b); }
; __device__ __forceinline__ void tr_load(const float* W, int N, int item, int lane, float (&wv)[32]) {
;     const int nblk = N / 32, kb = item / nblk, nb = item % nblk, k0 = 64 * kb, n0 = 32 * nb;
; #pragma unroll
;     for (int i = 0; i < 32; ++i) { const int kk = 2 * i + (lane >> 5); wv[i] = __builtin_nontemporal_load(W + (size_t)(k0 + kk) * N + n0 + (lane & 31)); }
; }
; template <int MAP, bool HASG, bool PERMW>
; __device__ __forceinline__ void tr_store(int K, int N, bf16_t* WT, LAS float* scr, int item, int lane, const float* gk) {
;     const int nblk = N / 32, kb = item / nblk, nb = item % nblk, k0 = 64 * kb, n0 = 32 * nb;
;     asm volatile("s_waitcnt lgkmcnt(0)" ::: "memory");
;     const int c = lane & 7;
;     f32x4 g0 = {1.f, 1.f, 1.f, 1.f}, g1 = {1.f, 1.f, 1.f, 1.f};
;     if (HASG) { g0 = *(const f32x4*)(gk + k0 + 8 * c); g1 = *(const f32x4*)(gk + k0 + 8 * c + 4); }
; #pragma unroll
;     for (int j = 0; j < 4; ++j) { const int n = (lane >> 3) + 8 * j; const LAS float* s = scr + (8 * c) * 33 + n;
;         u32x4 o; o.x = pk2(s[0 * 33] * g0[0], s[1 * 33] * g0[1]); o.y = pk2(s[2 * 33] * g0[2], s[3 * 33] * g0[3]); o.z = pk2(s[4 * 33] * g1[0], s[5 * 33] * g1[1]); o.w = pk2(s[6 * 33] * g1[2], s[7 * 33] * g1[3]);
;         const int wr_ = rowmap<MAP>(n0 + n), slot_ = PERMW ? ((wr_ & ~31) + invperm32(wr_ & 31)) : wr_;
;         *(u32x4*)((char*)WT + tiled_off(slot_, k0 + 8 * c, K / 64)) = o; }
; template <int MAP, bool HASG = false, bool PERMW = false>
; __device__ __forceinline__ void transpose_mat(const float* W, int K, int N, bf16_t* WT, LAS float* scr, int gw, int ngw, int lane, const float* gk = nullptr) {
;     ...
;     for (;;) {
;         __builtin_amdgcn_sched_barrier(0);
; #pragma unroll
;         for (int i = 0; i < 32; ++i) { const int kk = 2 * i + (lane >> 5); scr[kk * 33 + (lane & 31)] = wv[i]; }
;         __builtin_amdgcn_sched_barrier(0);
;         const int nx = it + ngw;
;         if (nx < nitems) tr_load(W, N, nx, lane, wv);
;         __builtin_amdgcn_sched_barrier(0);
;         tr_store<MAP, HASG, PERMW>(K, N, WT, scr, it, lane, gk);
;         if (nx >= nitems) break;
;         it = nx;
;     }
.LBB0_378:
	s_cmpk_lt_u32 s2, 0x80
	s_cbranch_scc1 .Ltc3_done
	v_writelane_b32 v255, s4, 24
	v_writelane_b32 v255, s5, 25
	v_writelane_b32 v255, s6, 26
	v_writelane_b32 v255, s7, 27
	v_writelane_b32 v255, s8, 28
	v_writelane_b32 v255, s9, 29
	v_writelane_b32 v255, s10, 30
	v_writelane_b32 v255, s11, 31
	v_writelane_b32 v255, s12, 32
	v_writelane_b32 v255, s13, 33
	v_writelane_b32 v255, s14, 34
	v_writelane_b32 v255, s15, 35
	v_writelane_b32 v255, s16, 36
	v_writelane_b32 v255, s17, 37
	v_writelane_b32 v255, s18, 38
	v_writelane_b32 v255, s19, 39
	v_readfirstlane_b32 s8, v234
	s_nop 3
	s_lshr_b32 s8, s8, 6
	s_sub_u32 s18, s2, 0x80
	s_lshl_b32 s18, s18, 3
	s_add_u32 s18, s18, s8
	s_mul_i32 s10, s8, 0x2100
	v_and_b32_e32 v0, 63, v234
	v_and_b32_e32 v1, 31, v0
	v_lshrrev_b32_e32 v2, 5, v0
	v_lshlrev_b32_e32 v3, 13, v2
	v_lshl_add_u32 v3, v1, 2, v3
	v_mul_u32_u24_e32 v4, 33, v2
	v_add_u32_e32 v4, v4, v1
	v_lshl_add_u32 v4, v4, 2, s10
	v_and_b32_e32 v5, 7, v0
	v_lshrrev_b32_e32 v6, 3, v0
	v_mul_u32_u24_e32 v7, 0x108, v5
	v_add_u32_e32 v7, v7, v6
	v_lshl_add_u32 v7, v7, 2, s10
	v_lshrrev_b32_e32 v12, 2, v5
	v_lshlrev_b32_e32 v12, 10, v12
	v_and_b32_e32 v13, 3, v5
	v_lshl_add_u32 v12, v13, 4, v12
	v_lshl_add_u32 v8, v6, 6, v12
	v_xor_b32_e32 v9, 32, v8
	v_add_u32_e32 v9, 0x200, v9
	v_and_b32_e32 v13, 3, v6
	v_lshl_add_u32 v10, v13, 6, v12
	v_bfe_u32 v13, v6, 2, 1
	v_lshl_add_u32 v10, v13, 11, v10
	v_xor_b32_e32 v11, 32, v10
	v_readlane_b32 s4, v255, 10
	v_readlane_b32 s5, v255, 11
	s_nop 3
	s_and_b32 s6, s60, 0x800000
	s_add_u32 s4, s4, s6
	s_addc_u32 s5, s5, 0
	s_add_u32 s6, s76, 0x7600000
	s_addc_u32 s7, s77, 0
	s_mov_b32 s9, s18
.Ltc3a_loop:
	s_cmpk_ge_u32 s9, 0x400
	s_cbranch_scc1 .Ltc3a_exit
	s_lshr_b32 s11, s9, 6
	s_and_b32 s12, s9, 63
	s_lshl_b32 s13, s11, 19
	s_lshl_b32 s14, s12, 7
	s_add_u32 s13, s13, s14
	s_add_u32 s14, s4, s13
	s_addc_u32 s15, s5, 0
	global_load_dword v16, v3, s[14:15] nt
	s_add_u32 s14, s14, 0x4000
	s_addc_u32 s15, s15, 0
	global_load_dword v17, v3, s[14:15] nt
	s_add_u32 s14, s14, 0x4000
	s_addc_u32 s15, s15, 0
	global_load_dword v18, v3, s[14:15] nt
	s_add_u32 s14, s14, 0x4000
	s_addc_u32 s15, s15, 0
	global_load_dword v19, v3, s[14:15] nt
	s_add_u32 s14, s14, 0x4000
	s_addc_u32 s15, s15, 0
	global_load_dword v20, v3, s[14:15] nt
	s_add_u32 s14, s14, 0x4000
	s_addc_u32 s15, s15, 0
	global_load_dword v21, v3, s[14:15] nt
	s_add_u32 s14, s14, 0x4000
	s_addc_u32 s15, s15, 0
	global_load_dword v22, v3, s[14:15] nt
	s_add_u32 s14, s14, 0x4000
	s_addc_u32 s15, s15, 0
	global_load_dword v23, v3, s[14:15] nt
	s_add_u32 s14, s14, 0x4000
	s_addc_u32 s15, s15, 0
	global_load_dword v24, v3, s[14:15] nt
	s_add_u32 s14, s14, 0x4000
	s_addc_u32 s15, s15, 0
	global_load_dword v25, v3, s[14:15] nt
	s_add_u32 s14, s14, 0x4000
	s_addc_u32 s15, s15, 0
	global_load_dword v26, v3, s[14:15] nt
	s_add_u32 s14, s14, 0x4000
	s_addc_u32 s15, s15, 0
	global_load_dword v27, v3, s[14:15] nt
	s_add_u32 s14, s14, 0x4000
	s_addc_u32 s15, s15, 0
	global_load_dword v28, v3, s[14:15] nt
	s_add_u32 s14, s14, 0x4000
	s_addc_u32 s15, s15, 0
	global_load_dword v29, v3, s[14:15] nt
	s_add_u32 s14, s14, 0x4000
	s_addc_u32 s15, s15, 0
	global_load_dword v30, v3, s[14:15] nt
	s_add_u32 s14, s14, 0x4000
	s_addc_u32 s15, s15, 0
	global_load_dword v31, v3, s[14:15] nt
	s_add_u32 s14, s14, 0x4000
	s_addc_u32 s15, s15, 0
	global_load_dword v32, v3, s[14:15] nt
	s_add_u32 s14, s14, 0x4000
	s_addc_u32 s15, s15, 0
	global_load_dword v33, v3, s[14:15] nt
	s_add_u32 s14, s14, 0x4000
	s_addc_u32 s15, s15, 0
	global_load_dword v34, v3, s[14:15] nt
	s_add_u32 s14, s14, 0x4000
	s_addc_u32 s15, s15, 0
	global_load_dword v35, v3, s[14:15] nt
	s_add_u32 s14, s14, 0x4000
	s_addc_u32 s15, s15, 0
	global_load_dword v36, v3, s[14:15] nt
	s_add_u32 s14, s14, 0x4000
	s_addc_u32 s15, s15, 0
	global_load_dword v37, v3, s[14:15] nt
	s_add_u32 s14, s14, 0x4000
	s_addc_u32 s15, s15, 0
	global_load_dword v38, v3, s[14:15] nt
	s_add_u32 s14, s14, 0x4000
	s_addc_u32 s15, s15, 0
	global_load_dword v39, v3, s[14:15] nt
	s_add_u32 s14, s14, 0x4000
	s_addc_u32 s15, s15, 0
	global_load_dword v40, v3, s[14:15] nt
	s_add_u32 s14, s14, 0x4000
	s_addc_u32 s15, s15, 0
	global_load_dword v41, v3, s[14:15] nt
	s_add_u32 s14, s14, 0x4000
	s_addc_u32 s15, s15, 0
	global_load_dword v42, v3, s[14:15] nt
	s_add_u32 s14, s14, 0x4000
	s_addc_u32 s15, s15, 0
	global_load_dword v43, v3, s[14:15] nt
	s_add_u32 s14, s14, 0x4000
	s_addc_u32 s15, s15, 0
	global_load_dword v44, v3, s[14:15] nt
	s_add_u32 s14, s14, 0x4000
	s_addc_u32 s15, s15, 0
	global_load_dword v45, v3, s[14:15] nt
	s_add_u32 s14, s14, 0x4000
	s_addc_u32 s15, s15, 0
	global_load_dword v46, v3, s[14:15] nt
	s_add_u32 s14, s14, 0x4000
	s_addc_u32 s15, s15, 0
	global_load_dword v47, v3, s[14:15] nt
	s_lshr_b32 s16, s12, 2
	s_mul_i32 s16, s16, 0x10
	s_add_u32 s16, s16, s11
	s_lshl_b32 s16, s16, 14
	s_and_b32 s17, s12, 3
	s_lshl_b32 s17, s17, 12
	s_add_u32 s16, s16, s17
	s_add_u32 s16, s6, s16
	s_addc_u32 s17, s7, 0
	s_waitcnt vmcnt(0)
	ds_write_b32 v4, v16
	ds_write_b32 v4, v17 offset:264
	ds_write_b32 v4, v18 offset:528
	ds_write_b32 v4, v19 offset:792
	ds_write_b32 v4, v20 offset:1056
	ds_write_b32 v4, v21 offset:1320
	ds_write_b32 v4, v22 offset:1584
	ds_write_b32 v4, v23 offset:1848
	ds_write_b32 v4, v24 offset:2112
	ds_write_b32 v4, v25 offset:2376
	ds_write_b32 v4, v26 offset:2640
	ds_write_b32 v4, v27 offset:2904
	ds_write_b32 v4, v28 offset:3168
	ds_write_b32 v4, v29 offset:3432
	ds_write_b32 v4, v30 offset:3696
	ds_write_b32 v4, v31 offset:3960
	ds_write_b32 v4, v32 offset:4224
	ds_write_b32 v4, v33 offset:4488
	ds_write_b32 v4, v34 offset:4752
	ds_write_b32 v4, v35 offset:5016
	ds_write_b32 v4, v36 offset:5280
	ds_write_b32 v4, v37 offset:5544
	ds_write_b32 v4, v38 offset:5808
	ds_write_b32 v4, v39 offset:6072
	ds_write_b32 v4, v40 offset:6336
	ds_write_b32 v4, v41 offset:6600
	ds_write_b32 v4, v42 offset:6864
	ds_write_b32 v4, v43 offset:7128
	ds_write_b32 v4, v44 offset:7392
	ds_write_b32 v4, v45 offset:7656
	ds_write_b32 v4, v46 offset:7920
	ds_write_b32 v4, v47 offset:8184
	s_waitcnt lgkmcnt(0)
; #define LAS __attribute__((address_space(3)))
; __device__ __forceinline__ void tr_load(const float* W, int N, int item, int lane, float (&wv)[32]) {
;     const int nblk = N / 32, kb = item / nblk, nb = item % nblk, k0 = 64 * kb, n0 = 32 * nb;
; #pragma unroll
;     for (int i = 0; i < 32; ++i) { const int kk = 2 * i + (lane >> 5); wv[i] = __builtin_nontemporal_load(W + (size_t)(k0 + kk) * N + n0 + (lane & 31)); }
; }
; template <int MAP, bool HASG, bool PERMW>
; __device__ __forceinline__ void tr_store(int K, int N, bf16_t* WT, LAS float* scr, int item, int lane, const float* gk) {
;     const int nblk = N / 32, kb = item / nblk, nb = item % nblk, k0 = 64 * kb, n0 = 32 * nb;
;     asm volatile("s_waitcnt lgkmcnt(0)" ::: "memory");
;     const int c = lane & 7;
;     f32x4 g0 = {1.f, 1.f, 1.f, 1.f}, g1 = {1.f, 1.f, 1.f, 1.f};
;     if (HASG) { g0 = *(const f32x4*)(gk + k0 + 8 * c); g1 = *(const f32x4*)(gk + k0 + 8 * c + 4); }
; #pragma unroll
;     for (int j = 0; j < 4; ++j) { const int n = (lane >> 3) + 8 * j; const LAS float* s = scr + (8 * c) * 33 + n;
;         u32x4 o; o.x = pk2(s[0 * 33] * g0[0], s[1 * 33] * g0[1]); o.y = pk2(s[2 * 33] * g0[2], s[3 * 33] * g0[3]); o.z = pk2(s[4 * 33] * g1[0], s[5 * 33] * g1[1]); o.w = pk2(s[6 * 33] * g1[2], s[7 * 33] * g1[3]);
;         const int wr_ = rowmap<MAP>(n0 + n), slot_ = PERMW ? ((wr_ & ~31) + invperm32(wr_ & 31)) : wr_;
;         *(u32x4*)((char*)WT + tiled_off(slot_, k0 + 8 * c, K / 64)) = o; }
;     asm volatile("s_waitcnt lgkmcnt(0)" ::: "memory");
; template <int MAP, bool HASG = false, bool PERMW = false>
; __device__ __forceinline__ void transpose_mat(const float* W, int K, int N, bf16_t* WT, LAS float* scr, int gw, int ngw, int lane, const float* gk = nullptr) {
;     ...
;     for (;;) {
;         __builtin_amdgcn_sched_barrier(0);
; #pragma unroll
;         for (int i = 0; i < 32; ++i) { const int kk = 2 * i + (lane >> 5); scr[kk * 33 + (lane & 31)] = wv[i]; }
;         __builtin_amdgcn_sched_barrier(0);
;         const int nx = it + ngw;
;         if (nx < nitems) tr_load(W, N, nx, lane, wv);
;         __builtin_amdgcn_sched_barrier(0);
;         tr_store<MAP, HASG, PERMW>(K, N, WT, scr, it, lane, gk);
;         if (nx >= nitems) break;
;         it = nx;
;     }
	ds_read_b32 v48, v7
	ds_read_b32 v49, v7 offset:132
	ds_read_b32 v50, v7 offset:264
	ds_read_b32 v51, v7 offset:396
	ds_read_b32 v52, v7 offset:528
	ds_read_b32 v53, v7 offset:660
	ds_read_b32 v54, v7 offset:792
	ds_read_b32 v55, v7 offset:924
	ds_read_b32 v56, v7 offset:32
	ds_read_b32 v57, v7 offset:164
	ds_read_b32 v58, v7 offset:296
	ds_read_b32 v59, v7 offset:428
	ds_read_b32 v60, v7 offset:560
	ds_read_b32 v61, v7 offset:692
	ds_read_b32 v62, v7 offset:824
	ds_read_b32 v63, v7 offset:956
	ds_read_b32 v64, v7 offset:64
	ds_read_b32 v65, v7 offset:196
	ds_read_b32 v66, v7 offset:328
	ds_read_b32 v67, v7 offset:460
	ds_read_b32 v68, v7 offset:592
	ds_read_b32 v69, v7 offset:724
	ds_read_b32 v70, v7 offset:856
	ds_read_b32 v71, v7 offset:988
	ds_read_b32 v72, v7 offset:96
	ds_read_b32 v73, v7 offset:228
	ds_read_b32 v74, v7 offset:360
	ds_read_b32 v75, v7 offset:492
	ds_read_b32 v76, v7 offset:624
	ds_read_b32 v77, v7 offset:756
	ds_read_b32 v78, v7 offset:888
	ds_read_b32 v79, v7 offset:1020
	s_waitcnt lgkmcnt(0)
	v_cvt_pk_bf16_f32 v48, v48, v49
	v_cvt_pk_bf16_f32 v49, v50, v51
	v_cvt_pk_bf16_f32 v50, v52, v53
	v_cvt_pk_bf16_f32 v51, v54, v55
	global_store_dwordx4 v10, v[48:51], s[16:17]
	v_cvt_pk_bf16_f32 v56, v56, v57
	v_cvt_pk_bf16_f32 v57, v58, v59
	v_cvt_pk_bf16_f32 v58, v60, v61
	v_cvt_pk_bf16_f32 v59, v62, v63
	global_store_dwordx4 v10, v[56:59], s[16:17] offset:256
	v_cvt_pk_bf16_f32 v64, v64, v65
	v_cvt_pk_bf16_f32 v65, v66, v67
	v_cvt_pk_bf16_f32 v66, v68, v69
	v_cvt_pk_bf16_f32 v67, v70, v71
	global_store_dwordx4 v11, v[64:67], s[16:17] offset:512
	v_cvt_pk_bf16_f32 v72, v72, v73
	v_cvt_pk_bf16_f32 v73, v74, v75
	v_cvt_pk_bf16_f32 v74, v76, v77
	v_cvt_pk_bf16_f32 v75, v78, v79
	global_store_dwordx4 v11, v[72:75], s[16:17] offset:768
	s_add_u32 s9, s9, 0x400
	s_branch .Ltc3a_loop
.Ltc3a_exit:
	v_readlane_b32 s4, v254, 0
	v_readlane_b32 s5, v254, 1
	s_nop 3
	s_and_b32 s6, s60, 0x1000000
	s_add_u32 s4, s4, s6
	s_addc_u32 s5, s5, 0
	s_add_u32 s6, s76, 0x7a00000
	s_addc_u32 s7, s77, 0
	s_mov_b32 s9, s18
.Ltc3b_loop:
	s_cmpk_ge_u32 s9, 0x800
	s_cbranch_scc1 .Ltc3b_exit
	s_lshr_b32 s11, s9, 6
	s_and_b32 s12, s9, 63
	s_lshl_b32 s13, s11, 19
	s_lshl_b32 s14, s12, 7
	s_add_u32 s13, s13, s14
	s_add_u32 s14, s4, s13
	s_addc_u32 s15, s5, 0
	global_load_dword v16, v3, s[14:15] nt
	s_add_u32 s14, s14, 0x4000
	s_addc_u32 s15, s15, 0
	global_load_dword v17, v3, s[14:15] nt
	s_add_u32 s14, s14, 0x4000
	s_addc_u32 s15, s15, 0
	global_load_dword v18, v3, s[14:15] nt
	s_add_u32 s14, s14, 0x4000
	s_addc_u32 s15, s15, 0
	global_load_dword v19, v3, s[14:15] nt
	s_add_u32 s14, s14, 0x4000
	s_addc_u32 s15, s15, 0
	global_load_dword v20, v3, s[14:15] nt
	s_add_u32 s14, s14, 0x4000
	s_addc_u32 s15, s15, 0
	global_load_dword v21, v3, s[14:15] nt
	s_add_u32 s14, s14, 0x4000
	s_addc_u32 s15, s15, 0
	global_load_dword v22, v3, s[14:15] nt
	s_add_u32 s14, s14, 0x4000
	s_addc_u32 s15, s15, 0
	global_load_dword v23, v3, s[14:15] nt
	s_add_u32 s14, s14, 0x4000
	s_addc_u32 s15, s15, 0
	global_load_dword v24, v3, s[14:15] nt
	s_add_u32 s14, s14, 0x4000
	s_addc_u32 s15, s15, 0
	global_load_dword v25, v3, s[14:15] nt
	s_add_u32 s14, s14, 0x4000
	s_addc_u32 s15, s15, 0
	global_load_dword v26, v3, s[14:15] nt
	s_add_u32 s14, s14, 0x4000
	s_addc_u32 s15, s15, 0
	global_load_dword v27, v3, s[14:15] nt
	s_add_u32 s14, s14, 0x4000
	s_addc_u32 s15, s15, 0
	global_load_dword v28, v3, s[14:15] nt
	s_add_u32 s14, s14, 0x4000
	s_addc_u32 s15, s15, 0
	global_load_dword v29, v3, s[14:15] nt
	s_add_u32 s14, s14, 0x4000
	s_addc_u32 s15, s15, 0
	global_load_dword v30, v3, s[14:15] nt
	s_add_u32 s14, s14, 0x4000
	s_addc_u32 s15, s15, 0
	global_load_dword v31, v3, s[14:15] nt
	s_add_u32 s14, s14, 0x4000
	s_addc_u32 s15, s15, 0
	global_load_dword v32, v3, s[14:15] nt
	s_add_u32 s14, s14, 0x4000
	s_addc_u32 s15, s15, 0
	global_load_dword v33, v3, s[14:15] nt
	s_add_u32 s14, s14, 0x4000
	s_addc_u32 s15, s15, 0
	global_load_dword v34, v3, s[14:15] nt
	s_add_u32 s14, s14, 0x4000
	s_addc_u32 s15, s15, 0
	global_load_dword v35, v3, s[14:15] nt
	s_add_u32 s14, s14, 0x4000
	s_addc_u32 s15, s15, 0
	global_load_dword v36, v3, s[14:15] nt
	s_add_u32 s14, s14, 0x4000
	s_addc_u32 s15, s15, 0
	global_load_dword v37, v3, s[14:15] nt
	s_add_u32 s14, s14, 0x4000
	s_addc_u32 s15, s15, 0
	global_load_dword v38, v3, s[14:15] nt
	s_add_u32 s14, s14, 0x4000
	s_addc_u32 s15, s15, 0
	global_load_dword v39, v3, s[14:15] nt
	s_add_u32 s14, s14, 0x4000
	s_addc_u32 s15, s15, 0
	global_load_dword v40, v3, s[14:15] nt
	s_add_u32 s14, s14, 0x4000
	s_addc_u32 s15, s15, 0
	global_load_dword v41, v3, s[14:15] nt
	s_add_u32 s14, s14, 0x4000
	s_addc_u32 s15, s15, 0
	global_load_dword v42, v3, s[14:15] nt
	s_add_u32 s14, s14, 0x4000
	s_addc_u32 s15, s15, 0
	global_load_dword v43, v3, s[14:15] nt
	s_add_u32 s14, s14, 0x4000
	s_addc_u32 s15, s15, 0
	global_load_dword v44, v3, s[14:15] nt
	s_add_u32 s14, s14, 0x4000
	s_addc_u32 s15, s15, 0
	global_load_dword v45, v3, s[14:15] nt
	s_add_u32 s14, s14, 0x4000
	s_addc_u32 s15, s15, 0
	global_load_dword v46, v3, s[14:15] nt
	s_add_u32 s14, s14, 0x4000
	s_addc_u32 s15, s15, 0
	global_load_dword v47, v3, s[14:15] nt
	s_lshr_b32 s16, s12, 2
	s_mul_i32 s16, s16, 0x20
	s_add_u32 s16, s16, s11
	s_lshl_b32 s16, s16, 14
	s_and_b32 s17, s12, 3
	s_lshl_b32 s17, s17, 12
	s_add_u32 s16, s16, s17
	s_add_u32 s16, s6, s16
	s_addc_u32 s17, s7, 0
	s_waitcnt vmcnt(0)
; #define LAS __attribute__((address_space(3)))
; __device__ __forceinline__ void tr_load(const float* W, int N, int item, int lane, float (&wv)[32]) {
;     const int nblk = N / 32, kb = item / nblk, nb = item % nblk, k0 = 64 * kb, n0 = 32 * nb;
; #pragma unroll
;     for (int i = 0; i < 32; ++i) { const int kk = 2 * i + (lane >> 5); wv[i] = __builtin_nontemporal_load(W + (size_t)(k0 + kk) * N + n0 + (lane & 31)); }
; }
; template <int MAP, bool HASG, bool PERMW>
; __device__ __forceinline__ void tr_store(int K, int N, bf16_t* WT, LAS float* scr, int item, int lane, const float* gk) {
;     const int nblk = N / 32, kb = item / nblk, nb = item % nblk, k0 = 64 * kb, n0 = 32 * nb;
;     asm volatile("s_waitcnt lgkmcnt(0)" ::: "memory");
;     const int c = lane & 7;
;     f32x4 g0 = {1.f, 1.f, 1.f, 1.f}, g1 = {1.f, 1.f, 1.f, 1.f};
;     if (HASG) { g0 = *(const f32x4*)(gk + k0 + 8 * c); g1 = *(const f32x4*)(gk + k0 + 8 * c + 4); }
; #pragma unroll
;     for (int j = 0; j < 4; ++j) { const int n = (lane >> 3) + 8 * j; const LAS float* s = scr + (8 * c) * 33 + n;
;         u32x4 o; o.x = pk2(s[0 * 33] * g0[0], s[1 * 33] * g0[1]); o.y = pk2(s[2 * 33] * g0[2], s[3 * 33] * g0[3]); o.z = pk2(s[4 * 33] * g1[0], s[5 * 33] * g1[1]); o.w = pk2(s[6 * 33] * g1[2], s[7 * 33] * g1[3]);
;         const int wr_ = rowmap<MAP>(n0 + n), slot_ = PERMW ? ((wr_ & ~31) + invperm32(wr_ & 31)) : wr_;
;         *(u32x4*)((char*)WT + tiled_off(slot_, k0 + 8 * c, K / 64)) = o; }
;     asm volatile("s_waitcnt lgkmcnt(0)" ::: "memory");
; template <int MAP, bool HASG = false, bool PERMW = false>
; __device__ __forceinline__ void transpose_mat(const float* W, int K, int N, bf16_t* WT, LAS float* scr, int gw, int ngw, int lane, const float* gk = nullptr) {
;     ...
;     for (;;) {
;         __builtin_amdgcn_sched_barrier(0);
; #pragma unroll
;         for (int i = 0; i < 32; ++i) { const int kk = 2 * i + (lane >> 5); scr[kk * 33 + (lane & 31)] = wv[i]; }
;         __builtin_amdgcn_sched_barrier(0);
;         const int nx = it + ngw;
;         if (nx < nitems) tr_load(W, N, nx, lane, wv);
;         __builtin_amdgcn_sched_barrier(0);
;         tr_store<MAP, HASG, PERMW>(K, N, WT, scr, it, lane, gk);
;         if (nx >= nitems) break;
;         it = nx;
;     }
	ds_write_b32 v4, v16
	ds_write_b32 v4, v17 offset:264
	ds_write_b32 v4, v18 offset:528
	ds_write_b32 v4, v19 offset:792
	ds_write_b32 v4, v20 offset:1056
	ds_write_b32 v4, v21 offset:1320
	ds_write_b32 v4, v22 offset:1584
	ds_write_b32 v4, v23 offset:1848
	ds_write_b32 v4, v24 offset:2112
	ds_write_b32 v4, v25 offset:2376
	ds_write_b32 v4, v26 offset:2640
	ds_write_b32 v4, v27 offset:2904
	ds_write_b32 v4, v28 offset:3168
	ds_write_b32 v4, v29 offset:3432
	ds_write_b32 v4, v30 offset:3696
	ds_write_b32 v4, v31 offset:3960
	ds_write_b32 v4, v32 offset:4224
	ds_write_b32 v4, v33 offset:4488
	ds_write_b32 v4, v34 offset:4752
	ds_write_b32 v4, v35 offset:5016
	ds_write_b32 v4, v36 offset:5280
	ds_write_b32 v4, v37 offset:5544
	ds_write_b32 v4, v38 offset:5808
	ds_write_b32 v4, v39 offset:6072
	ds_write_b32 v4, v40 offset:6336
	ds_write_b32 v4, v41 offset:6600
	ds_write_b32 v4, v42 offset:6864
	ds_write_b32 v4, v43 offset:7128
	ds_write_b32 v4, v44 offset:7392
	ds_write_b32 v4, v45 offset:7656
	ds_write_b32 v4, v46 offset:7920
	ds_write_b32 v4, v47 offset:8184
	s_waitcnt lgkmcnt(0)
	ds_read_b32 v48, v7
	ds_read_b32 v49, v7 offset:132
	ds_read_b32 v50, v7 offset:264
	ds_read_b32 v51, v7 offset:396
	ds_read_b32 v52, v7 offset:528
	ds_read_b32 v53, v7 offset:660
	ds_read_b32 v54, v7 offset:792
	ds_read_b32 v55, v7 offset:924
	ds_read_b32 v56, v7 offset:32
	ds_read_b32 v57, v7 offset:164
	ds_read_b32 v58, v7 offset:296
	ds_read_b32 v59, v7 offset:428
	ds_read_b32 v60, v7 offset:560
	ds_read_b32 v61, v7 offset:692
	ds_read_b32 v62, v7 offset:824
	ds_read_b32 v63, v7 offset:956
	ds_read_b32 v64, v7 offset:64
	ds_read_b32 v65, v7 offset:196
	ds_read_b32 v66, v7 offset:328
	ds_read_b32 v67, v7 offset:460
	ds_read_b32 v68, v7 offset:592
	ds_read_b32 v69, v7 offset:724
	ds_read_b32 v70, v7 offset:856
	ds_read_b32 v71, v7 offset:988
	ds_read_b32 v72, v7 offset:96
	ds_read_b32 v73, v7 offset:228
	ds_read_b32 v74, v7 offset:360
	ds_read_b32 v75, v7 offset:492
	ds_read_b32 v76, v7 offset:624
	ds_read_b32 v77, v7 offset:756
	ds_read_b32 v78, v7 offset:888
	ds_read_b32 v79, v7 offset:1020
	s_waitcnt lgkmcnt(0)
	v_cvt_pk_bf16_f32 v48, v48, v49
	v_cvt_pk_bf16_f32 v49, v50, v51
	v_cvt_pk_bf16_f32 v50, v52, v53
	v_cvt_pk_bf16_f32 v51, v54, v55
	global_store_dwordx4 v10, v[48:51], s[16:17]
	v_cvt_pk_bf16_f32 v56, v56, v57
	v_cvt_pk_bf16_f32 v57, v58, v59
	v_cvt_pk_bf16_f32 v58, v60, v61
	v_cvt_pk_bf16_f32 v59, v62, v63
	global_store_dwordx4 v10, v[56:59], s[16:17] offset:256
	v_cvt_pk_bf16_f32 v64, v64, v65
	v_cvt_pk_bf16_f32 v65, v66, v67
	v_cvt_pk_bf16_f32 v66, v68, v69
	v_cvt_pk_bf16_f32 v67, v70, v71
	global_store_dwordx4 v11, v[64:67], s[16:17] offset:512
	v_cvt_pk_bf16_f32 v72, v72, v73
	v_cvt_pk_bf16_f32 v73, v74, v75
	v_cvt_pk_bf16_f32 v74, v76, v77
	v_cvt_pk_bf16_f32 v75, v78, v79
	global_store_dwordx4 v11, v[72:75], s[16:17] offset:768
	s_add_u32 s9, s9, 0x400
	s_branch .Ltc3b_loop
.Ltc3b_exit:
	v_readlane_b32 s4, v254, 2
	v_readlane_b32 s5, v254, 3
	s_nop 3
	s_and_b32 s6, s60, 0x1000000
	s_add_u32 s4, s4, s6
	s_addc_u32 s5, s5, 0
	s_add_u32 s6, s76, 0x8200000
	s_addc_u32 s7, s77, 0
	s_mov_b32 s9, s18
.Ltc3c_loop:
	s_cmpk_ge_u32 s9, 0x800
	s_cbranch_scc1 .Ltc3c_exit
	s_lshr_b32 s11, s9, 6
	s_and_b32 s12, s9, 63
	s_lshl_b32 s13, s11, 19
	s_lshl_b32 s14, s12, 7
	s_add_u32 s13, s13, s14
	s_add_u32 s14, s4, s13
	s_addc_u32 s15, s5, 0
	global_load_dword v16, v3, s[14:15] nt
	s_add_u32 s14, s14, 0x4000
	s_addc_u32 s15, s15, 0
	global_load_dword v17, v3, s[14:15] nt
	s_add_u32 s14, s14, 0x4000
	s_addc_u32 s15, s15, 0
	global_load_dword v18, v3, s[14:15] nt
	s_add_u32 s14, s14, 0x4000
	s_addc_u32 s15, s15, 0
	global_load_dword v19, v3, s[14:15] nt
	s_add_u32 s14, s14, 0x4000
	s_addc_u32 s15, s15, 0
	global_load_dword v20, v3, s[14:15] nt
	s_add_u32 s14, s14, 0x4000
	s_addc_u32 s15, s15, 0
	global_load_dword v21, v3, s[14:15] nt
	s_add_u32 s14, s14, 0x4000
	s_addc_u32 s15, s15, 0
	global_load_dword v22, v3, s[14:15] nt
	s_add_u32 s14, s14, 0x4000
	s_addc_u32 s15, s15, 0
	global_load_dword v23, v3, s[14:15] nt
	s_add_u32 s14, s14, 0x4000
	s_addc_u32 s15, s15, 0
	global_load_dword v24, v3, s[14:15] nt
	s_add_u32 s14, s14, 0x4000
	s_addc_u32 s15, s15, 0
	global_load_dword v25, v3, s[14:15] nt
	s_add_u32 s14, s14, 0x4000
	s_addc_u32 s15, s15, 0
	global_load_dword v26, v3, s[14:15] nt
	s_add_u32 s14, s14, 0x4000
	s_addc_u32 s15, s15, 0
	global_load_dword v27, v3, s[14:15] nt
	s_add_u32 s14, s14, 0x4000
	s_addc_u32 s15, s15, 0
	global_load_dword v28, v3, s[14:15] nt
	s_add_u32 s14, s14, 0x4000
	s_addc_u32 s15, s15, 0
	global_load_dword v29, v3, s[14:15] nt
	s_add_u32 s14, s14, 0x4000
	s_addc_u32 s15, s15, 0
	global_load_dword v30, v3, s[14:15] nt
	s_add_u32 s14, s14, 0x4000
	s_addc_u32 s15, s15, 0
	global_load_dword v31, v3, s[14:15] nt
	s_add_u32 s14, s14, 0x4000
	s_addc_u32 s15, s15, 0
	global_load_dword v32, v3, s[14:15] nt
	s_add_u32 s14, s14, 0x4000
	s_addc_u32 s15, s15, 0
	global_load_dword v33, v3, s[14:15] nt
	s_add_u32 s14, s14, 0x4000
	s_addc_u32 s15, s15, 0
	global_load_dword v34, v3, s[14:15] nt
	s_add_u32 s14, s14, 0x4000
	s_addc_u32 s15, s15, 0
	global_load_dword v35, v3, s[14:15] nt
	s_add_u32 s14, s14, 0x4000
	s_addc_u32 s15, s15, 0
	global_load_dword v36, v3, s[14:15] nt
	s_add_u32 s14, s14, 0x4000
	s_addc_u32 s15, s15, 0
	global_load_dword v37, v3, s[14:15] nt
	s_add_u32 s14, s14, 0x4000
	s_addc_u32 s15, s15, 0
	global_load_dword v38, v3, s[14:15] nt
	s_add_u32 s14, s14, 0x4000
	s_addc_u32 s15, s15, 0
	global_load_dword v39, v3, s[14:15] nt
	s_add_u32 s14, s14, 0x4000
	s_addc_u32 s15, s15, 0
	global_load_dword v40, v3, s[14:15] nt
	s_add_u32 s14, s14, 0x4000
	s_addc_u32 s15, s15, 0
	global_load_dword v41, v3, s[14:15] nt
	s_add_u32 s14, s14, 0x4000
	s_addc_u32 s15, s15, 0
	global_load_dword v42, v3, s[14:15] nt
	s_add_u32 s14, s14, 0x4000
	s_addc_u32 s15, s15, 0
	global_load_dword v43, v3, s[14:15] nt
	s_add_u32 s14, s14, 0x4000
	s_addc_u32 s15, s15, 0
	global_load_dword v44, v3, s[14:15] nt
	s_add_u32 s14, s14, 0x4000
	s_addc_u32 s15, s15, 0
	global_load_dword v45, v3, s[14:15] nt
	s_add_u32 s14, s14, 0x4000
	s_addc_u32 s15, s15, 0
	global_load_dword v46, v3, s[14:15] nt
	s_add_u32 s14, s14, 0x4000
	s_addc_u32 s15, s15, 0
	global_load_dword v47, v3, s[14:15] nt
	s_lshr_b32 s16, s12, 2
	s_mul_i32 s16, s16, 0x20
	s_add_u32 s16, s16, s11
	s_lshl_b32 s16, s16, 14
	s_and_b32 s17, s12, 3
	s_lshl_b32 s17, s17, 12
	s_add_u32 s16, s16, s17
	s_add_u32 s16, s6, s16
	s_addc_u32 s17, s7, 0
	s_waitcnt vmcnt(0)
; #define LAS __attribute__((address_space(3)))
; __device__ __forceinline__ unsigned pk2(float lo, float hi) { f32x2 f = {lo, hi}; bf16x2_t b = __builtin_convertvector(f, bf16x2_t); return __builtin_bit_cast(unsigned, b); }
; __device__ __forceinline__ unsigned xb_xcc_id() { return (unsigned)__builtin_amdgcn_s_getreg((3 << 11) | 20) & 0xFu; }
; __device__ __forceinline__ void xcd_barrier(unsigned char* ws_base, volatile LAS unsigned* st) {
;     asm volatile("s_waitcnt vmcnt(0)" ::: "memory");
;     __syncthreads();
;     if (threadIdx.x == 0) {
;         unsigned long long a = (unsigned long long)(ws_base + WS_CTL);
;         asm volatile("" : "+s"(a));
;         unsigned* bar = (unsigned*)a;
;         const unsigned x = xb_xcc_id();
;         __builtin_amdgcn_s_waitcnt(0);
;         unsigned nloc = st[0], nx = st[1];
;         if (nloc == 0u) { xcd_barrier_complete(bar, x, nloc, nx); st[0] = nloc; st[1] = nx; }
; template <int MAP, bool HASG, bool PERMW>
; __device__ __forceinline__ void tr_store(int K, int N, bf16_t* WT, LAS float* scr, int item, int lane, const float* gk) {
;     ...
;     const int c = lane & 7;
;     f32x4 g0 = {1.f, 1.f, 1.f, 1.f}, g1 = {1.f, 1.f, 1.f, 1.f};
;     if (HASG) { g0 = *(const f32x4*)(gk + k0 + 8 * c); g1 = *(const f32x4*)(gk + k0 + 8 * c + 4); }
; #pragma unroll
;     for (int j = 0; j < 4; ++j) { const int n = (lane >> 3) + 8 * j; const LAS float* s = scr + (8 * c) * 33 + n;
;         u32x4 o; o.x = pk2(s[0 * 33] * g0[0], s[1 * 33] * g0[1]); o.y = pk2(s[2 * 33] * g0[2], s[3 * 33] * g0[3]); o.z = pk2(s[4 * 33] * g1[0], s[5 * 33] * g1[1]); o.w = pk2(s[6 * 33] * g1[2], s[7 * 33] * g1[3]);
;         const int wr_ = rowmap<MAP>(n0 + n), slot_ = PERMW ? ((wr_ & ~31) + invperm32(wr_ & 31)) : wr_;
;         *(u32x4*)((char*)WT + tiled_off(slot_, k0 + 8 * c, K / 64)) = o; }
;     asm volatile("s_waitcnt lgkmcnt(0)" ::: "memory");
	ds_write_b32 v4, v16
	ds_write_b32 v4, v17 offset:264
	ds_write_b32 v4, v18 offset:528
	ds_write_b32 v4, v19 offset:792
	ds_write_b32 v4, v20 offset:1056
	ds_write_b32 v4, v21 offset:1320
	ds_write_b32 v4, v22 offset:1584
	ds_write_b32 v4, v23 offset:1848
	ds_write_b32 v4, v24 offset:2112
	ds_write_b32 v4, v25 offset:2376
	ds_write_b32 v4, v26 offset:2640
	ds_write_b32 v4, v27 offset:2904
	ds_write_b32 v4, v28 offset:3168
	ds_write_b32 v4, v29 offset:3432
	ds_write_b32 v4, v30 offset:3696
	ds_write_b32 v4, v31 offset:3960
	ds_write_b32 v4, v32 offset:4224
	ds_write_b32 v4, v33 offset:4488
	ds_write_b32 v4, v34 offset:4752
	ds_write_b32 v4, v35 offset:5016
	ds_write_b32 v4, v36 offset:5280
	ds_write_b32 v4, v37 offset:5544
	ds_write_b32 v4, v38 offset:5808
	ds_write_b32 v4, v39 offset:6072
	ds_write_b32 v4, v40 offset:6336
	ds_write_b32 v4, v41 offset:6600
	ds_write_b32 v4, v42 offset:6864
	ds_write_b32 v4, v43 offset:7128
	ds_write_b32 v4, v44 offset:7392
	ds_write_b32 v4, v45 offset:7656
	ds_write_b32 v4, v46 offset:7920
	ds_write_b32 v4, v47 offset:8184
	s_waitcnt lgkmcnt(0)
	ds_read_b32 v48, v7
	ds_read_b32 v49, v7 offset:132
	ds_read_b32 v50, v7 offset:264
	ds_read_b32 v51, v7 offset:396
	ds_read_b32 v52, v7 offset:528
	ds_read_b32 v53, v7 offset:660
	ds_read_b32 v54, v7 offset:792
	ds_read_b32 v55, v7 offset:924
	ds_read_b32 v56, v7 offset:32
	ds_read_b32 v57, v7 offset:164
	ds_read_b32 v58, v7 offset:296
	ds_read_b32 v59, v7 offset:428
	ds_read_b32 v60, v7 offset:560
	ds_read_b32 v61, v7 offset:692
	ds_read_b32 v62, v7 offset:824
	ds_read_b32 v63, v7 offset:956
	ds_read_b32 v64, v7 offset:64
	ds_read_b32 v65, v7 offset:196
	ds_read_b32 v66, v7 offset:328
	ds_read_b32 v67, v7 offset:460
	ds_read_b32 v68, v7 offset:592
	ds_read_b32 v69, v7 offset:724
	ds_read_b32 v70, v7 offset:856
	ds_read_b32 v71, v7 offset:988
	ds_read_b32 v72, v7 offset:96
	ds_read_b32 v73, v7 offset:228
	ds_read_b32 v74, v7 offset:360
	ds_read_b32 v75, v7 offset:492
	ds_read_b32 v76, v7 offset:624
	ds_read_b32 v77, v7 offset:756
	ds_read_b32 v78, v7 offset:888
	ds_read_b32 v79, v7 offset:1020
	s_waitcnt lgkmcnt(0)
	v_cvt_pk_bf16_f32 v48, v48, v49
	v_cvt_pk_bf16_f32 v49, v50, v51
	v_cvt_pk_bf16_f32 v50, v52, v53
	v_cvt_pk_bf16_f32 v51, v54, v55
	global_store_dwordx4 v8, v[48:51], s[16:17]
	v_cvt_pk_bf16_f32 v56, v56, v57
	v_cvt_pk_bf16_f32 v57, v58, v59
	v_cvt_pk_bf16_f32 v58, v60, v61
	v_cvt_pk_bf16_f32 v59, v62, v63
	global_store_dwordx4 v9, v[56:59], s[16:17]
	v_cvt_pk_bf16_f32 v64, v64, v65
	v_cvt_pk_bf16_f32 v65, v66, v67
	v_cvt_pk_bf16_f32 v66, v68, v69
	v_cvt_pk_bf16_f32 v67, v70, v71
	global_store_dwordx4 v8, v[64:67], s[16:17] offset:2048
	v_cvt_pk_bf16_f32 v72, v72, v73
	v_cvt_pk_bf16_f32 v73, v74, v75
	v_cvt_pk_bf16_f32 v74, v76, v77
	v_cvt_pk_bf16_f32 v75, v78, v79
	global_store_dwordx4 v9, v[72:75], s[16:17] offset:2048
	s_add_u32 s9, s9, 0x400
	s_branch .Ltc3c_loop
.Ltc3c_exit:
	v_readlane_b32 s4, v255, 24
	v_readlane_b32 s5, v255, 25
	v_readlane_b32 s6, v255, 26
	v_readlane_b32 s7, v255, 27
	v_readlane_b32 s8, v255, 28
	v_readlane_b32 s9, v255, 29
	v_readlane_b32 s10, v255, 30
	v_readlane_b32 s11, v255, 31
	v_readlane_b32 s12, v255, 32
	v_readlane_b32 s13, v255, 33
	v_readlane_b32 s14, v255, 34
	v_readlane_b32 s15, v255, 35
	v_readlane_b32 s16, v255, 36
	v_readlane_b32 s17, v255, 37
	v_readlane_b32 s18, v255, 38
	v_readlane_b32 s19, v255, 39
	s_nop 3
.Ltc3_done:
	s_waitcnt vmcnt(0)
	s_waitcnt vmcnt(0) lgkmcnt(0)
	s_barrier
	s_mov_b64 s[40:41], exec
	v_readlane_b32 s0, v254, 16
	v_readlane_b32 s1, v254, 17
	s_and_b64 s[0:1], s[40:41], s[0:1]
	s_mov_b64 exec, s[0:1]
	s_cbranch_execz .LBB0_422
	v_readlane_b32 s1, v255, 17
	s_mov_b64 s[14:15], s[96:97]
	s_getreg_b32 s0, hwreg(HW_REG_XCC_ID, 0, 4)
	v_mov_b32_e32 v0, s1
	s_waitcnt vmcnt(0) expcnt(0) lgkmcnt(0)
	ds_read_b32 v2, v0
	v_readlane_b32 s1, v255, 18
	s_and_b32 s4, s0, 15
	s_waitcnt lgkmcnt(0)
	v_cmp_ne_u32_e32 vcc, 0, v2
	v_mov_b32_e32 v0, s1
	ds_read_b32 v0, v0
	s_cbranch_vccnz .LBB0_393
	s_add_u32 s0, s14, 0x1000
	s_addc_u32 s1, s15, 0
	s_add_u32 s6, s14, 0x1100
	s_addc_u32 s7, s15, 0
	s_add_u32 s8, s14, 0x1200
	s_addc_u32 s9, s15, 0
	s_add_u32 s10, s14, 0x1300
	s_addc_u32 s11, s15, 0
	s_mov_b32 s5, 1
	s_mov_b64 s[16:17], 0
	s_branch .LBB0_383

; #define LAS __attribute__((address_space(3)))
; __device__ __forceinline__ unsigned pk2(float lo, float hi) { f32x2 f = {lo, hi}; bf16x2_t b = __builtin_convertvector(f, bf16x2_t); return __builtin_bit_cast(unsigned, b); }
; __device__ __forceinline__ size_t tiled_off(int row, int col, int nkt) {
;     return ((size_t)(row >> 7) * nkt + (col >> 6)) * 16384 + (size_t)pg8::lds_byte(row & 127, col & 63);
; }
; template <int MAP, bool HASG, bool PERMW>
; __device__ __forceinline__ void tr_store(int K, int N, bf16_t* WT, LAS float* scr, int item, int lane, const float* gk) {
;     const int nblk = N / 32, kb = item / nblk, nb = item % nblk, k0 = 64 * kb, n0 = 32 * nb;
;     asm volatile("s_waitcnt lgkmcnt(0)" ::: "memory");
;     const int c = lane & 7;
;     f32x4 g0 = {1.f, 1.f, 1.f, 1.f}, g1 = {1.f, 1.f, 1.f, 1.f};
;     if (HASG) { g0 = *(const f32x4*)(gk + k0 + 8 * c); g1 = *(const f32x4*)(gk + k0 + 8 * c + 4); }
; #pragma unroll
;     for (int j = 0; j < 4; ++j) { const int n = (lane >> 3) + 8 * j; const LAS float* s = scr + (8 * c) * 33 + n;
;         u32x4 o; o.x = pk2(s[0 * 33] * g0[0], s[1 * 33] * g0[1]); o.y = pk2(s[2 * 33] * g0[2], s[3 * 33] * g0[3]); o.z = pk2(s[4 * 33] * g1[0], s[5 * 33] * g1[1]); o.w = pk2(s[6 * 33] * g1[2], s[7 * 33] * g1[3]);
;         const int wr_ = rowmap<MAP>(n0 + n), slot_ = PERMW ? ((wr_ & ~31) + invperm32(wr_ & 31)) : wr_;
;         *(u32x4*)((char*)WT + tiled_off(slot_, k0 + 8 * c, K / 64)) = o; }
.LBB0_826:
	s_cmpk_lt_u32 s2, 0x80
	s_cbranch_scc1 .Ltc2_done
	v_writelane_b32 v255, s4, 24
	v_writelane_b32 v255, s5, 25
	v_writelane_b32 v255, s6, 26
	v_writelane_b32 v255, s7, 27
	v_writelane_b32 v255, s8, 28
	v_writelane_b32 v255, s9, 29
	v_writelane_b32 v255, s10, 30
	v_writelane_b32 v255, s11, 31
	v_writelane_b32 v255, s12, 32
	v_writelane_b32 v255, s13, 33
	v_writelane_b32 v255, s14, 34
	v_writelane_b32 v255, s15, 35
	v_writelane_b32 v255, s16, 36
	v_writelane_b32 v255, s17, 37
	v_writelane_b32 v255, s18, 38
	v_writelane_b32 v255, s19, 39
	v_readfirstlane_b32 s8, v234
	s_nop 3
	s_lshr_b32 s8, s8, 6
	s_sub_u32 s18, s2, 0x80
	s_lshl_b32 s18, s18, 3
	s_add_u32 s18, s18, s8
	s_mul_i32 s10, s8, 0x2100
	v_and_b32_e32 v0, 63, v234
	v_and_b32_e32 v1, 31, v0
	v_lshrrev_b32_e32 v2, 5, v0
	v_lshlrev_b32_e32 v3, 13, v2
	v_lshl_add_u32 v3, v1, 2, v3
	v_mul_u32_u24_e32 v4, 33, v2
	v_add_u32_e32 v4, v4, v1
	v_lshl_add_u32 v4, v4, 2, s10
	v_and_b32_e32 v5, 7, v0
	v_lshrrev_b32_e32 v6, 3, v0
	v_mul_u32_u24_e32 v7, 0x108, v5
	v_add_u32_e32 v7, v7, v6
	v_lshl_add_u32 v7, v7, 2, s10
	v_lshrrev_b32_e32 v12, 2, v5
	v_lshlrev_b32_e32 v12, 10, v12
	v_and_b32_e32 v13, 3, v5
	v_lshl_add_u32 v12, v13, 4, v12
	v_lshl_add_u32 v8, v6, 6, v12
	v_xor_b32_e32 v9, 32, v8
	v_add_u32_e32 v9, 0x200, v9
	v_and_b32_e32 v13, 3, v6
	v_lshl_add_u32 v10, v13, 6, v12
	v_bfe_u32 v13, v6, 2, 1
	v_lshl_add_u32 v10, v13, 11, v10
	v_xor_b32_e32 v11, 32, v10
	v_readlane_b32 s4, v254, 10
	v_readlane_b32 s5, v254, 11
	s_nop 3
	s_and_b32 s6, s60, 0x2c00000
	s_add_u32 s4, s4, s6
	s_addc_u32 s5, s5, 0
	s_add_u32 s6, s76, 0xb600000
	s_addc_u32 s7, s77, 0
	s_mov_b32 s9, s18
